# role alternation phases +3/+5: 75% of the 16-unit blocks reordered
# baseline (speedup 1.0000x reference)
; #define SUB(k, bit) (!(kargs()->li == 1 && (k) == lo) || ((kargs()->submask >> (bit)) & 1u))
; __global__ void __launch_bounds__(NWAVES * 64, 2) fwd(Args args_unused) {
;     ...
;         if (IN(pb + 3)) {
;             PH_PTRS PH_LAYER
;             if (SUB(pb + 3, 0)) {
.LBB0_1364:
	v_readlane_b32 s99, v254, 3
	s_nop 3
	s_lshr_b32 s99, s99, 4
	s_and_b32 s99, s99, 3
	s_mov_b32 s98, 2
	s_cmp_eq_u32 s99, 1
	s_cselect_b32 s98, 0, s98
	s_cmp_eq_u32 s99, 2
	s_cselect_b32 s98, 0, s98
	s_cmp_eq_u32 s99, 3
	s_cselect_b32 s98, 0, s98
